# pass-2 tails: the eight mask words of a stage go out with one LDS write (v_writelane of the ballot halves) instead of four exec-masked two-lane writes; candidate path trimmed (32-bit key add, 2-op mon
# speedup vs baseline: 1.0114x; 1.0114x over previous
.LBB0_1024:
	v_mov_b32_e32 v246, v149
	v_add_u32_e32 v247, 0x471, v246
	v_lshlrev_b32_e32 v247, 19, v247
	v_sub_u32_e32 v248, 0x86f, v246
	v_lshlrev_b32_e32 v248, 19, v248
	v_add_u32_e32 v248, 0x7fffffff, v248
	v_cmp_lt_i32_e32 vcc, 0x1ff, v246
	s_nop 1
	v_cndmask_b32_e32 v250, v248, v247, vcc
	v_cmp_ne_u32_e32 vcc, 0x1ff, v246
	s_nop 1
	v_cndmask_b32_e32 v250, 0, v250, vcc
	v_cmp_ne_u32_e32 vcc, 0x3ff, v246
	v_mov_b32_e32 v249, 0x7fc00000
	s_nop 0
	v_cndmask_b32_e32 v250, v249, v250, vcc
	v_cmp_le_i32_e32 vcc, 0, v246
	s_nop 1
	v_mov_b32_e32 v249, s33
	v_cndmask_b32_e32 v250, v249, v250, vcc
	v_add_u32_e32 v246, -1, v149
	v_add_u32_e32 v247, 0x471, v246
	v_lshlrev_b32_e32 v247, 19, v247
	v_sub_u32_e32 v248, 0x86f, v246
	v_lshlrev_b32_e32 v248, 19, v248
	v_add_u32_e32 v248, 0x7fffffff, v248
	v_cmp_lt_i32_e32 vcc, 0x1ff, v246
	s_nop 1
	v_cndmask_b32_e32 v156, v248, v247, vcc
	v_cmp_ne_u32_e32 vcc, 0x1ff, v246
	s_nop 1
	v_cndmask_b32_e32 v156, 0, v156, vcc
	v_cmp_ne_u32_e32 vcc, 0x3ff, v246
	v_mov_b32_e32 v249, 0x7fc00000
	s_nop 0
	v_cndmask_b32_e32 v156, v249, v156, vcc
	v_cmp_le_i32_e32 vcc, 0, v246
	s_nop 1
	v_mov_b32_e32 v249, s33
	v_cndmask_b32_e32 v156, v249, v156, vcc
	v_mov_b32_e32 v246, v159
	v_add_u32_e32 v247, 0x471, v246
	v_lshlrev_b32_e32 v247, 19, v247
	v_sub_u32_e32 v248, 0x86f, v246
	v_lshlrev_b32_e32 v248, 19, v248
	v_add_u32_e32 v248, 0x7fffffff, v248
	v_cmp_lt_i32_e32 vcc, 0x1ff, v246
	s_nop 1
	v_cndmask_b32_e32 v197, v248, v247, vcc
	v_cmp_ne_u32_e32 vcc, 0x1ff, v246
	s_nop 1
	v_cndmask_b32_e32 v197, 0, v197, vcc
	v_cmp_ne_u32_e32 vcc, 0x3ff, v246
	v_mov_b32_e32 v249, 0x7fc00000
	s_nop 0
	v_cndmask_b32_e32 v197, v249, v197, vcc
	v_cmp_le_i32_e32 vcc, 0, v246
	s_nop 1
	v_mov_b32_e32 v249, s33
	v_cndmask_b32_e32 v197, v249, v197, vcc
	v_add_u32_e32 v246, -1, v159
	v_add_u32_e32 v247, 0x471, v246
	v_lshlrev_b32_e32 v247, 19, v247
	v_sub_u32_e32 v248, 0x86f, v246
	v_lshlrev_b32_e32 v248, 19, v248
	v_add_u32_e32 v248, 0x7fffffff, v248
	v_cmp_lt_i32_e32 vcc, 0x1ff, v246
	s_nop 1
	v_cndmask_b32_e32 v157, v248, v247, vcc
	v_cmp_ne_u32_e32 vcc, 0x1ff, v246
	s_nop 1
	v_cndmask_b32_e32 v157, 0, v157, vcc
	v_cmp_ne_u32_e32 vcc, 0x3ff, v246
	v_mov_b32_e32 v249, 0x7fc00000
	s_nop 0
	v_cndmask_b32_e32 v157, v249, v157, vcc
	v_cmp_le_i32_e32 vcc, 0, v246
	s_nop 1
	v_mov_b32_e32 v249, s33
	v_cndmask_b32_e32 v157, v249, v157, vcc
	v_readlane_b32 s4, v162, 0
	v_readlane_b32 s5, v162, 32
	v_and_b32_e32 v246, 1, v196
	v_lshlrev_b32_e32 v246, 2, v246
	v_bfe_u32 v247, v196, 1, 1
	v_lshl_add_u32 v246, v247, 10, v246
	v_mov_b32_e32 v247, s5
	v_mov_b32_e32 v248, s4
	v_and_b32_e32 v249, 4, v196
	v_cmp_ne_u32_e32 vcc, 0, v249
	s_nop 1
	v_cndmask_b32_e32 v248, v248, v247, vcc
	v_add_u32_e32 v162, v248, v246
	v_lshlrev_b32_e32 v246, 2, v196
	v_add_u32_e32 v246, 0x800, v246
	v_add_u32_e32 v246, v247, v246
	v_cmp_lt_u32_e32 vcc, 7, v196
	s_nop 1
	v_cndmask_b32_e32 v162, v162, v246, vcc
	ds_read_b128 v[164:167], v99 offset:0
	ds_read_b128 v[168:171], v99 offset:4096
	ds_read_b128 v[172:175], v99 offset:1024
	ds_read_b128 v[176:179], v99 offset:5120
	ds_read_b128 v[230:233], v99 offset:2048
	ds_read_b128 v[234:237], v99 offset:6144
	ds_read_b128 v[238:241], v99 offset:3072
	ds_read_b128 v[242:245], v99 offset:7168
	s_waitcnt lgkmcnt(7)
	v_mfma_f32_32x32x16_bf16 v[16:31], v[34:37], v[164:167], 0
	s_waitcnt lgkmcnt(6)
	v_mfma_f32_32x32x16_bf16 v[0:15], v[34:37], v[168:171], 0
	s_waitcnt vmcnt(3)
	ds_write_b128 v140, v[50:53] offset:8192
	s_add_i32 s4, s18, 5
	s_min_i32 s4, s4, s14
	v_mad_i64_i32 v[164:165], s[4:5], s4, v193, v[116:117]
	global_load_dwordx4 v[50:53], v[164:165], off
	s_waitcnt lgkmcnt(6)
	v_mfma_f32_32x32x16_bf16 v[16:31], v[38:41], v[172:175], v[16:31]
	s_waitcnt lgkmcnt(5)
	v_mfma_f32_32x32x16_bf16 v[0:15], v[38:41], v[176:179], v[0:15]
	s_waitcnt lgkmcnt(4)
	v_mfma_f32_32x32x16_bf16 v[16:31], v[42:45], v[230:233], v[16:31]
	s_waitcnt lgkmcnt(3)
	v_mfma_f32_32x32x16_bf16 v[0:15], v[42:45], v[234:237], v[0:15]
	s_waitcnt lgkmcnt(2)
	v_mfma_f32_32x32x16_bf16 v[16:31], v[46:49], v[238:241], v[16:31]
	s_waitcnt lgkmcnt(1)
	v_mfma_f32_32x32x16_bf16 v[0:15], v[46:49], v[242:245], v[0:15]
	s_waitcnt lgkmcnt(0)
	s_barrier
	s_add_u32 s18, s18, 1
	s_cmp_ge_u32 s18, s13
	s_cbranch_scc1 .Lp2_drain0
.Lp2_c1:
	ds_read_b128 v[164:167], v99 offset:8192
	ds_read_b128 v[168:171], v99 offset:12288
	ds_read_b128 v[172:175], v99 offset:9216
	ds_read_b128 v[176:179], v99 offset:13312
	ds_read_b128 v[230:233], v99 offset:10240
	ds_read_b128 v[234:237], v99 offset:14336
	ds_read_b128 v[238:241], v99 offset:11264
	ds_read_b128 v[242:245], v99 offset:15360
	v_max_i32_e32 v246, 0, v24
	v_max_i32_e32 v247, 0, v16
	v_max_i32_e32 v248, 0, v25
	v_max_i32_e32 v249, 0, v17
	s_waitcnt lgkmcnt(7)
	v_mfma_f32_32x32x16_bf16 v[198:213], v[34:37], v[164:167], 0
	v_fma_f32 v184, v100, v246, 0
	v_fma_f32 v185, v101, v247, 0
	v_fmac_f32_e32 v184, v102, v248
	v_fmac_f32_e32 v185, v103, v249
	v_max_i32_e32 v246, 0, v26
	v_max_i32_e32 v247, 0, v18
	v_max_i32_e32 v248, 0, v27
	v_max_i32_e32 v249, 0, v19
	v_fmac_f32_e32 v184, v104, v246
	v_fmac_f32_e32 v185, v105, v247
	s_waitcnt lgkmcnt(6)
	v_mfma_f32_32x32x16_bf16 v[214:229], v[34:37], v[168:171], 0
	s_waitcnt vmcnt(3)
	ds_write_b128 v140, v[54:57]
	s_add_i32 s4, s18, 5
	s_min_i32 s4, s4, s14
	v_mad_i64_i32 v[164:165], s[4:5], s4, v193, v[116:117]
	global_load_dwordx4 v[54:57], v[164:165], off
	v_fmac_f32_e32 v184, v106, v248
	v_fmac_f32_e32 v185, v107, v249
	v_max_i32_e32 v246, 0, v28
	v_max_i32_e32 v247, 0, v20
	v_max_i32_e32 v248, 0, v29
	v_max_i32_e32 v249, 0, v21
	v_fmac_f32_e32 v184, v108, v246
	v_fmac_f32_e32 v185, v109, v247
	v_fmac_f32_e32 v184, v110, v248
	v_fmac_f32_e32 v185, v111, v249
	s_waitcnt lgkmcnt(6)
	v_mfma_f32_32x32x16_bf16 v[198:213], v[38:41], v[172:175], v[198:213]
	v_max_i32_e32 v246, 0, v30
	v_max_i32_e32 v247, 0, v22
	v_max_i32_e32 v248, 0, v31
	v_max_i32_e32 v249, 0, v23
	v_fmac_f32_e32 v184, v112, v246
	v_fmac_f32_e32 v185, v113, v247
	v_fmac_f32_e32 v184, v114, v248
	v_fmac_f32_e32 v185, v115, v249
	s_waitcnt lgkmcnt(5)
	v_mfma_f32_32x32x16_bf16 v[214:229], v[38:41], v[176:179], v[214:229]
	v_cmp_le_f32_e64 s[52:53], v250, v185
	v_cmp_le_f32_e32 vcc, v156, v185
	s_andn2_b64 vcc, vcc, s[52:53]
	v_writelane_b32 v33, s52, 0
	v_writelane_b32 v33, s53, 4
	s_cbranch_vccz .Lp2_skip1
	v_mov_b32_e32 v246, vcc_hi
	v_mov_b32_e32 v247, vcc_lo
	v_cndmask_b32_e64 v246, v246, v247, s[48:49]
	s_and_saveexec_b64 s[4:5], vcc
	v_and_b32_e32 v247, v246, v127
	v_bcnt_u32_b32 v247, v247, v119
	v_cmp_gt_u32_e32 vcc, s35, v247
	v_ashrrev_i32_e32 v248, 31, v185
	v_add_u32_e32 v154, s0, v78
	v_bitop3_b32 v155, v185, v248, s97 bitop3:0x1e
	v_lshl_add_u32 v248, v247, 3, v160
	s_and_b64 exec, exec, vcc
	ds_write_b64 v248, v[154:155] offset:2048
	s_mov_b64 exec, s[4:5]
	v_bcnt_u32_b32 v119, v246, v119
.Lp2_skip1:
	s_waitcnt lgkmcnt(4)
	v_mfma_f32_32x32x16_bf16 v[198:213], v[42:45], v[230:233], v[198:213]
	v_cmp_le_f32_e64 s[52:53], v197, v184
	v_cmp_le_f32_e32 vcc, v157, v184
	s_andn2_b64 vcc, vcc, s[52:53]
	v_writelane_b32 v33, s52, 2
	v_writelane_b32 v33, s53, 6
	s_cbranch_vccz .Lp2_skip2
	v_mov_b32_e32 v246, vcc_hi
	v_mov_b32_e32 v247, vcc_lo
	v_cndmask_b32_e64 v246, v246, v247, s[48:49]
	s_and_saveexec_b64 s[4:5], vcc
	v_and_b32_e32 v247, v246, v127
	v_bcnt_u32_b32 v247, v247, v118
	v_cmp_gt_u32_e32 vcc, s35, v247
	v_ashrrev_i32_e32 v248, 31, v184
	v_add_u32_e32 v154, s0, v78
	v_bitop3_b32 v155, v184, v248, s97 bitop3:0x1e
	v_lshl_add_u32 v248, v247, 3, v161
	s_and_b64 exec, exec, vcc
	ds_write_b64 v248, v[154:155] offset:2048
	s_mov_b64 exec, s[4:5]
	v_bcnt_u32_b32 v118, v246, v118
.Lp2_skip2:
	v_max_i32_e32 v246, 0, v8
	v_max_i32_e32 v247, 0, v0
	s_waitcnt lgkmcnt(3)
	v_mfma_f32_32x32x16_bf16 v[214:229], v[42:45], v[234:237], v[214:229]
	v_max_i32_e32 v248, 0, v9
	v_max_i32_e32 v249, 0, v1
	v_fma_f32 v184, v100, v246, 0
	v_fma_f32 v185, v101, v247, 0
	v_fmac_f32_e32 v184, v102, v248
	v_fmac_f32_e32 v185, v103, v249
	v_max_i32_e32 v246, 0, v10
	v_max_i32_e32 v247, 0, v2
	v_max_i32_e32 v248, 0, v11
	v_max_i32_e32 v249, 0, v3
	s_waitcnt lgkmcnt(2)
	v_mfma_f32_32x32x16_bf16 v[198:213], v[46:49], v[238:241], v[198:213]
	v_fmac_f32_e32 v184, v104, v246
	v_fmac_f32_e32 v185, v105, v247
	v_fmac_f32_e32 v184, v106, v248
	v_fmac_f32_e32 v185, v107, v249
	v_max_i32_e32 v246, 0, v12
	v_max_i32_e32 v247, 0, v4
	v_max_i32_e32 v248, 0, v13
	v_max_i32_e32 v249, 0, v5
	v_fmac_f32_e32 v184, v108, v246
	v_fmac_f32_e32 v185, v109, v247
	s_waitcnt lgkmcnt(1)
	v_mfma_f32_32x32x16_bf16 v[214:229], v[46:49], v[242:245], v[214:229]
	v_fmac_f32_e32 v184, v110, v248
	v_fmac_f32_e32 v185, v111, v249
	v_max_i32_e32 v246, 0, v14
	v_max_i32_e32 v247, 0, v6
	v_max_i32_e32 v248, 0, v15
	v_max_i32_e32 v249, 0, v7
	v_fmac_f32_e32 v184, v112, v246
	v_fmac_f32_e32 v185, v113, v247
	v_fmac_f32_e32 v184, v114, v248
	v_fmac_f32_e32 v185, v115, v249
	v_cmp_le_f32_e64 s[52:53], v250, v185
	v_cmp_le_f32_e32 vcc, v156, v185
	s_andn2_b64 vcc, vcc, s[52:53]
	v_writelane_b32 v33, s52, 1
	v_writelane_b32 v33, s53, 5
	s_cbranch_vccz .Lp2_skip3
	v_mov_b32_e32 v246, vcc_hi
	v_mov_b32_e32 v247, vcc_lo
	v_cndmask_b32_e64 v246, v246, v247, s[48:49]
	s_and_saveexec_b64 s[4:5], vcc
	v_and_b32_e32 v247, v246, v127
	v_bcnt_u32_b32 v247, v247, v119
	v_cmp_gt_u32_e32 vcc, s35, v247
	v_ashrrev_i32_e32 v248, 31, v185
	v_add_u32_e32 v154, s0, v96
	v_bitop3_b32 v155, v185, v248, s97 bitop3:0x1e
	v_lshl_add_u32 v248, v247, 3, v160
	s_and_b64 exec, exec, vcc
	ds_write_b64 v248, v[154:155] offset:2048
	s_mov_b64 exec, s[4:5]
	v_bcnt_u32_b32 v119, v246, v119
.Lp2_skip3:
	v_cmp_le_f32_e64 s[52:53], v197, v184
	v_cmp_le_f32_e32 vcc, v157, v184
	s_andn2_b64 vcc, vcc, s[52:53]
	v_writelane_b32 v33, s52, 3
	v_writelane_b32 v33, s53, 7
	s_cbranch_vccz .Lp2_skip4
	v_mov_b32_e32 v246, vcc_hi
	v_mov_b32_e32 v247, vcc_lo
	v_cndmask_b32_e64 v246, v246, v247, s[48:49]
	s_and_saveexec_b64 s[4:5], vcc
	v_and_b32_e32 v247, v246, v127
	v_bcnt_u32_b32 v247, v247, v118
	v_cmp_gt_u32_e32 vcc, s35, v247
	v_ashrrev_i32_e32 v248, 31, v184
	v_add_u32_e32 v154, s0, v96
	v_bitop3_b32 v155, v184, v248, s97 bitop3:0x1e
	v_lshl_add_u32 v248, v247, 3, v161
	s_and_b64 exec, exec, vcc
	ds_write_b64 v248, v[154:155] offset:2048
	s_mov_b64 exec, s[4:5]
	v_bcnt_u32_b32 v118, v246, v118
.Lp2_skip4:
	ds_write_b32 v162, v33
	v_add_u32_e32 v162, 8, v162
	s_waitcnt lgkmcnt(0)
	s_barrier
	s_add_u32 s18, s18, 1
	s_cmp_ge_u32 s18, s13
	s_cbranch_scc1 .Lp2_drain1
.Lp2_c2:
	ds_read_b128 v[164:167], v99 offset:0
	ds_read_b128 v[168:171], v99 offset:4096
	ds_read_b128 v[172:175], v99 offset:1024
	ds_read_b128 v[176:179], v99 offset:5120
	ds_read_b128 v[230:233], v99 offset:2048
	ds_read_b128 v[234:237], v99 offset:6144
	ds_read_b128 v[238:241], v99 offset:3072
	ds_read_b128 v[242:245], v99 offset:7168
	v_max_i32_e32 v246, 0, v206
	v_max_i32_e32 v247, 0, v198
	v_max_i32_e32 v248, 0, v207
	v_max_i32_e32 v249, 0, v199
	s_waitcnt lgkmcnt(7)
	v_mfma_f32_32x32x16_bf16 v[16:31], v[34:37], v[164:167], 0
	v_fma_f32 v184, v100, v246, 0
	v_fma_f32 v185, v101, v247, 0
	v_fmac_f32_e32 v184, v102, v248
	v_fmac_f32_e32 v185, v103, v249
	v_max_i32_e32 v246, 0, v208
	v_max_i32_e32 v247, 0, v200
	v_max_i32_e32 v248, 0, v209
	v_max_i32_e32 v249, 0, v201
	v_fmac_f32_e32 v184, v104, v246
	v_fmac_f32_e32 v185, v105, v247
	s_waitcnt lgkmcnt(6)
	v_mfma_f32_32x32x16_bf16 v[0:15], v[34:37], v[168:171], 0
	s_waitcnt vmcnt(3)
	ds_write_b128 v140, v[58:61] offset:8192
	s_add_i32 s4, s18, 5
	s_min_i32 s4, s4, s14
	v_mad_i64_i32 v[164:165], s[4:5], s4, v193, v[116:117]
	global_load_dwordx4 v[58:61], v[164:165], off
	v_fmac_f32_e32 v184, v106, v248
	v_fmac_f32_e32 v185, v107, v249
	v_max_i32_e32 v246, 0, v210
	v_max_i32_e32 v247, 0, v202
	v_max_i32_e32 v248, 0, v211
	v_max_i32_e32 v249, 0, v203
	v_fmac_f32_e32 v184, v108, v246
	v_fmac_f32_e32 v185, v109, v247
	v_fmac_f32_e32 v184, v110, v248
	v_fmac_f32_e32 v185, v111, v249
	s_waitcnt lgkmcnt(6)
	v_mfma_f32_32x32x16_bf16 v[16:31], v[38:41], v[172:175], v[16:31]
	v_max_i32_e32 v246, 0, v212
	v_max_i32_e32 v247, 0, v204
	v_max_i32_e32 v248, 0, v213
	v_max_i32_e32 v249, 0, v205
	v_fmac_f32_e32 v184, v112, v246
	v_fmac_f32_e32 v185, v113, v247
	v_fmac_f32_e32 v184, v114, v248
	v_fmac_f32_e32 v185, v115, v249
	s_waitcnt lgkmcnt(5)
	v_mfma_f32_32x32x16_bf16 v[0:15], v[38:41], v[176:179], v[0:15]
	v_cmp_le_f32_e64 s[52:53], v250, v185
	v_cmp_le_f32_e32 vcc, v156, v185
	s_andn2_b64 vcc, vcc, s[52:53]
	v_writelane_b32 v33, s52, 0
	v_writelane_b32 v33, s53, 4
	s_cbranch_vccz .Lp2_skip5
	v_mov_b32_e32 v246, vcc_hi
	v_mov_b32_e32 v247, vcc_lo
	v_cndmask_b32_e64 v246, v246, v247, s[48:49]
	s_and_saveexec_b64 s[4:5], vcc
	v_and_b32_e32 v247, v246, v127
	v_bcnt_u32_b32 v247, v247, v119
	v_cmp_gt_u32_e32 vcc, s35, v247
	v_ashrrev_i32_e32 v248, 31, v185
	v_add_u32_e32 v154, s0, v92
	v_bitop3_b32 v155, v185, v248, s97 bitop3:0x1e
	v_lshl_add_u32 v248, v247, 3, v160
	s_and_b64 exec, exec, vcc
	ds_write_b64 v248, v[154:155] offset:2048
	s_mov_b64 exec, s[4:5]
	v_bcnt_u32_b32 v119, v246, v119
.Lp2_skip5:
	s_waitcnt lgkmcnt(4)
	v_mfma_f32_32x32x16_bf16 v[16:31], v[42:45], v[230:233], v[16:31]
	v_cmp_le_f32_e64 s[52:53], v197, v184
	v_cmp_le_f32_e32 vcc, v157, v184
	s_andn2_b64 vcc, vcc, s[52:53]
	v_writelane_b32 v33, s52, 2
	v_writelane_b32 v33, s53, 6
	s_cbranch_vccz .Lp2_skip6
	v_mov_b32_e32 v246, vcc_hi
	v_mov_b32_e32 v247, vcc_lo
	v_cndmask_b32_e64 v246, v246, v247, s[48:49]
	s_and_saveexec_b64 s[4:5], vcc
	v_and_b32_e32 v247, v246, v127
	v_bcnt_u32_b32 v247, v247, v118
	v_cmp_gt_u32_e32 vcc, s35, v247
	v_ashrrev_i32_e32 v248, 31, v184
	v_add_u32_e32 v154, s0, v92
	v_bitop3_b32 v155, v184, v248, s97 bitop3:0x1e
	v_lshl_add_u32 v248, v247, 3, v161
	s_and_b64 exec, exec, vcc
	ds_write_b64 v248, v[154:155] offset:2048
	s_mov_b64 exec, s[4:5]
	v_bcnt_u32_b32 v118, v246, v118
.Lp2_skip6:
	v_max_i32_e32 v246, 0, v222
	v_max_i32_e32 v247, 0, v214
	s_waitcnt lgkmcnt(3)
	v_mfma_f32_32x32x16_bf16 v[0:15], v[42:45], v[234:237], v[0:15]
	v_max_i32_e32 v248, 0, v223
	v_max_i32_e32 v249, 0, v215
	v_fma_f32 v184, v100, v246, 0
	v_fma_f32 v185, v101, v247, 0
	v_fmac_f32_e32 v184, v102, v248
	v_fmac_f32_e32 v185, v103, v249
	v_max_i32_e32 v246, 0, v224
	v_max_i32_e32 v247, 0, v216
	v_max_i32_e32 v248, 0, v225
	v_max_i32_e32 v249, 0, v217
	s_waitcnt lgkmcnt(2)
	v_mfma_f32_32x32x16_bf16 v[16:31], v[46:49], v[238:241], v[16:31]
	v_fmac_f32_e32 v184, v104, v246
	v_fmac_f32_e32 v185, v105, v247
	v_fmac_f32_e32 v184, v106, v248
	v_fmac_f32_e32 v185, v107, v249
	v_max_i32_e32 v246, 0, v226
	v_max_i32_e32 v247, 0, v218
	v_max_i32_e32 v248, 0, v227
	v_max_i32_e32 v249, 0, v219
	v_fmac_f32_e32 v184, v108, v246
	v_fmac_f32_e32 v185, v109, v247
	s_waitcnt lgkmcnt(1)
	v_mfma_f32_32x32x16_bf16 v[0:15], v[46:49], v[242:245], v[0:15]
	v_fmac_f32_e32 v184, v110, v248
	v_fmac_f32_e32 v185, v111, v249
	v_max_i32_e32 v246, 0, v228
	v_max_i32_e32 v247, 0, v220
	v_max_i32_e32 v248, 0, v229
	v_max_i32_e32 v249, 0, v221
	v_fmac_f32_e32 v184, v112, v246
	v_fmac_f32_e32 v185, v113, v247
	v_fmac_f32_e32 v184, v114, v248
	v_fmac_f32_e32 v185, v115, v249
	v_cmp_le_f32_e64 s[52:53], v250, v185
	v_cmp_le_f32_e32 vcc, v156, v185
	s_andn2_b64 vcc, vcc, s[52:53]
	v_writelane_b32 v33, s52, 1
	v_writelane_b32 v33, s53, 5
	s_cbranch_vccz .Lp2_skip7
	v_mov_b32_e32 v246, vcc_hi
	v_mov_b32_e32 v247, vcc_lo
	v_cndmask_b32_e64 v246, v246, v247, s[48:49]
	s_and_saveexec_b64 s[4:5], vcc
	v_and_b32_e32 v247, v246, v127
	v_bcnt_u32_b32 v247, v247, v119
	v_cmp_gt_u32_e32 vcc, s35, v247
	v_ashrrev_i32_e32 v248, 31, v185
	v_add_u32_e32 v154, s0, v94
	v_bitop3_b32 v155, v185, v248, s97 bitop3:0x1e
	v_lshl_add_u32 v248, v247, 3, v160
	s_and_b64 exec, exec, vcc
	ds_write_b64 v248, v[154:155] offset:2048
	s_mov_b64 exec, s[4:5]
	v_bcnt_u32_b32 v119, v246, v119
.Lp2_skip7:
	v_cmp_le_f32_e64 s[52:53], v197, v184
	v_cmp_le_f32_e32 vcc, v157, v184
	s_andn2_b64 vcc, vcc, s[52:53]
	v_writelane_b32 v33, s52, 3
	v_writelane_b32 v33, s53, 7
	s_cbranch_vccz .Lp2_skip8
	v_mov_b32_e32 v246, vcc_hi
	v_mov_b32_e32 v247, vcc_lo
	v_cndmask_b32_e64 v246, v246, v247, s[48:49]
	s_and_saveexec_b64 s[4:5], vcc
	v_and_b32_e32 v247, v246, v127
	v_bcnt_u32_b32 v247, v247, v118
	v_cmp_gt_u32_e32 vcc, s35, v247
	v_ashrrev_i32_e32 v248, 31, v184
	v_add_u32_e32 v154, s0, v94
	v_bitop3_b32 v155, v184, v248, s97 bitop3:0x1e
	v_lshl_add_u32 v248, v247, 3, v161
	s_and_b64 exec, exec, vcc
	ds_write_b64 v248, v[154:155] offset:2048
	s_mov_b64 exec, s[4:5]
	v_bcnt_u32_b32 v118, v246, v118

.Lp2_c3:
	ds_read_b128 v[164:167], v99 offset:8192
	ds_read_b128 v[168:171], v99 offset:12288
	ds_read_b128 v[172:175], v99 offset:9216
	ds_read_b128 v[176:179], v99 offset:13312
	ds_read_b128 v[230:233], v99 offset:10240
	ds_read_b128 v[234:237], v99 offset:14336
	ds_read_b128 v[238:241], v99 offset:11264
	ds_read_b128 v[242:245], v99 offset:15360
	v_max_i32_e32 v246, 0, v24
	v_max_i32_e32 v247, 0, v16
	v_max_i32_e32 v248, 0, v25
	v_max_i32_e32 v249, 0, v17
	s_waitcnt lgkmcnt(7)
	v_mfma_f32_32x32x16_bf16 v[198:213], v[34:37], v[164:167], 0
	v_fma_f32 v184, v100, v246, 0
	v_fma_f32 v185, v101, v247, 0
	v_fmac_f32_e32 v184, v102, v248
	v_fmac_f32_e32 v185, v103, v249
	v_max_i32_e32 v246, 0, v26
	v_max_i32_e32 v247, 0, v18
	v_max_i32_e32 v248, 0, v27
	v_max_i32_e32 v249, 0, v19
	v_fmac_f32_e32 v184, v104, v246
	v_fmac_f32_e32 v185, v105, v247
	s_waitcnt lgkmcnt(6)
	v_mfma_f32_32x32x16_bf16 v[214:229], v[34:37], v[168:171], 0
	s_waitcnt vmcnt(3)
	ds_write_b128 v140, v[62:65]
	s_add_i32 s4, s18, 5
	s_min_i32 s4, s4, s14
	v_mad_i64_i32 v[164:165], s[4:5], s4, v193, v[116:117]
	global_load_dwordx4 v[62:65], v[164:165], off
	v_fmac_f32_e32 v184, v106, v248
	v_fmac_f32_e32 v185, v107, v249
	v_max_i32_e32 v246, 0, v28
	v_max_i32_e32 v247, 0, v20
	v_max_i32_e32 v248, 0, v29
	v_max_i32_e32 v249, 0, v21
	v_fmac_f32_e32 v184, v108, v246
	v_fmac_f32_e32 v185, v109, v247
	v_fmac_f32_e32 v184, v110, v248
	v_fmac_f32_e32 v185, v111, v249
	s_waitcnt lgkmcnt(6)
	v_mfma_f32_32x32x16_bf16 v[198:213], v[38:41], v[172:175], v[198:213]
	v_max_i32_e32 v246, 0, v30
	v_max_i32_e32 v247, 0, v22
	v_max_i32_e32 v248, 0, v31
	v_max_i32_e32 v249, 0, v23
	v_fmac_f32_e32 v184, v112, v246
	v_fmac_f32_e32 v185, v113, v247
	v_fmac_f32_e32 v184, v114, v248
	v_fmac_f32_e32 v185, v115, v249
	s_waitcnt lgkmcnt(5)
	v_mfma_f32_32x32x16_bf16 v[214:229], v[38:41], v[176:179], v[214:229]
	v_cmp_le_f32_e64 s[52:53], v250, v185
	v_cmp_le_f32_e32 vcc, v156, v185
	s_andn2_b64 vcc, vcc, s[52:53]
	v_writelane_b32 v33, s52, 0
	v_writelane_b32 v33, s53, 4
	s_cbranch_vccz .Lp2_skip9
	v_mov_b32_e32 v246, vcc_hi
	v_mov_b32_e32 v247, vcc_lo
	v_cndmask_b32_e64 v246, v246, v247, s[48:49]
	s_and_saveexec_b64 s[4:5], vcc
	v_and_b32_e32 v247, v246, v127
	v_bcnt_u32_b32 v247, v247, v119
	v_cmp_gt_u32_e32 vcc, s35, v247
	v_ashrrev_i32_e32 v248, 31, v185
	v_add_u32_e32 v154, s0, v90
	v_bitop3_b32 v155, v185, v248, s97 bitop3:0x1e
	v_lshl_add_u32 v248, v247, 3, v160
	s_and_b64 exec, exec, vcc
	ds_write_b64 v248, v[154:155] offset:2048
	s_mov_b64 exec, s[4:5]
	v_bcnt_u32_b32 v119, v246, v119
.Lp2_skip9:
	s_waitcnt lgkmcnt(4)
	v_mfma_f32_32x32x16_bf16 v[198:213], v[42:45], v[230:233], v[198:213]
	v_cmp_le_f32_e64 s[52:53], v197, v184
	v_cmp_le_f32_e32 vcc, v157, v184
	s_andn2_b64 vcc, vcc, s[52:53]
	v_writelane_b32 v33, s52, 2
	v_writelane_b32 v33, s53, 6
	s_cbranch_vccz .Lp2_skip10
	v_mov_b32_e32 v246, vcc_hi
	v_mov_b32_e32 v247, vcc_lo
	v_cndmask_b32_e64 v246, v246, v247, s[48:49]
	s_and_saveexec_b64 s[4:5], vcc
	v_and_b32_e32 v247, v246, v127
	v_bcnt_u32_b32 v247, v247, v118
	v_cmp_gt_u32_e32 vcc, s35, v247
	v_ashrrev_i32_e32 v248, 31, v184
	v_add_u32_e32 v154, s0, v90
	v_bitop3_b32 v155, v184, v248, s97 bitop3:0x1e
	v_lshl_add_u32 v248, v247, 3, v161
	s_and_b64 exec, exec, vcc
	ds_write_b64 v248, v[154:155] offset:2048
	s_mov_b64 exec, s[4:5]
	v_bcnt_u32_b32 v118, v246, v118
.Lp2_skip10:
	v_max_i32_e32 v246, 0, v8
	v_max_i32_e32 v247, 0, v0
	s_waitcnt lgkmcnt(3)
	v_mfma_f32_32x32x16_bf16 v[214:229], v[42:45], v[234:237], v[214:229]
	v_max_i32_e32 v248, 0, v9
	v_max_i32_e32 v249, 0, v1
	v_fma_f32 v184, v100, v246, 0
	v_fma_f32 v185, v101, v247, 0
	v_fmac_f32_e32 v184, v102, v248
	v_fmac_f32_e32 v185, v103, v249
	v_max_i32_e32 v246, 0, v10
	v_max_i32_e32 v247, 0, v2
	v_max_i32_e32 v248, 0, v11
	v_max_i32_e32 v249, 0, v3
	s_waitcnt lgkmcnt(2)
	v_mfma_f32_32x32x16_bf16 v[198:213], v[46:49], v[238:241], v[198:213]
	v_fmac_f32_e32 v184, v104, v246
	v_fmac_f32_e32 v185, v105, v247
	v_fmac_f32_e32 v184, v106, v248
	v_fmac_f32_e32 v185, v107, v249
	v_max_i32_e32 v246, 0, v12
	v_max_i32_e32 v247, 0, v4
	v_max_i32_e32 v248, 0, v13
	v_max_i32_e32 v249, 0, v5
	v_fmac_f32_e32 v184, v108, v246
	v_fmac_f32_e32 v185, v109, v247
	s_waitcnt lgkmcnt(1)
	v_mfma_f32_32x32x16_bf16 v[214:229], v[46:49], v[242:245], v[214:229]
	v_fmac_f32_e32 v184, v110, v248
	v_fmac_f32_e32 v185, v111, v249
	v_max_i32_e32 v246, 0, v14
	v_max_i32_e32 v247, 0, v6
	v_max_i32_e32 v248, 0, v15
	v_max_i32_e32 v249, 0, v7
	v_fmac_f32_e32 v184, v112, v246
	v_fmac_f32_e32 v185, v113, v247
	v_fmac_f32_e32 v184, v114, v248
	v_fmac_f32_e32 v185, v115, v249
	v_cmp_le_f32_e64 s[52:53], v250, v185
	v_cmp_le_f32_e32 vcc, v156, v185
	s_andn2_b64 vcc, vcc, s[52:53]
	v_writelane_b32 v33, s52, 1
	v_writelane_b32 v33, s53, 5
	s_cbranch_vccz .Lp2_skip11
	v_mov_b32_e32 v246, vcc_hi
	v_mov_b32_e32 v247, vcc_lo
	v_cndmask_b32_e64 v246, v246, v247, s[48:49]
	s_and_saveexec_b64 s[4:5], vcc
	v_and_b32_e32 v247, v246, v127
	v_bcnt_u32_b32 v247, v247, v119
	v_cmp_gt_u32_e32 vcc, s35, v247
	v_ashrrev_i32_e32 v248, 31, v185
	v_add_u32_e32 v154, s0, v88
	v_bitop3_b32 v155, v185, v248, s97 bitop3:0x1e
	v_lshl_add_u32 v248, v247, 3, v160
	s_and_b64 exec, exec, vcc
	ds_write_b64 v248, v[154:155] offset:2048
	s_mov_b64 exec, s[4:5]
	v_bcnt_u32_b32 v119, v246, v119
.Lp2_skip11:
	v_cmp_le_f32_e64 s[52:53], v197, v184
	v_cmp_le_f32_e32 vcc, v157, v184
	s_andn2_b64 vcc, vcc, s[52:53]
	v_writelane_b32 v33, s52, 3
	v_writelane_b32 v33, s53, 7
	s_cbranch_vccz .Lp2_skip12
	v_mov_b32_e32 v246, vcc_hi
	v_mov_b32_e32 v247, vcc_lo
	v_cndmask_b32_e64 v246, v246, v247, s[48:49]
	s_and_saveexec_b64 s[4:5], vcc
	v_and_b32_e32 v247, v246, v127
	v_bcnt_u32_b32 v247, v247, v118
	v_cmp_gt_u32_e32 vcc, s35, v247
	v_ashrrev_i32_e32 v248, 31, v184
	v_add_u32_e32 v154, s0, v88
	v_bitop3_b32 v155, v184, v248, s97 bitop3:0x1e
	v_lshl_add_u32 v248, v247, 3, v161
	s_and_b64 exec, exec, vcc
	ds_write_b64 v248, v[154:155] offset:2048
	s_mov_b64 exec, s[4:5]
	v_bcnt_u32_b32 v118, v246, v118

.Lp2_c0:
	ds_read_b128 v[164:167], v99 offset:0
	ds_read_b128 v[168:171], v99 offset:4096
	ds_read_b128 v[172:175], v99 offset:1024
	ds_read_b128 v[176:179], v99 offset:5120
	ds_read_b128 v[230:233], v99 offset:2048
	ds_read_b128 v[234:237], v99 offset:6144
	ds_read_b128 v[238:241], v99 offset:3072
	ds_read_b128 v[242:245], v99 offset:7168
	v_max_i32_e32 v246, 0, v206
	v_max_i32_e32 v247, 0, v198
	v_max_i32_e32 v248, 0, v207
	v_max_i32_e32 v249, 0, v199
	s_waitcnt lgkmcnt(7)
	v_mfma_f32_32x32x16_bf16 v[16:31], v[34:37], v[164:167], 0
	v_fma_f32 v184, v100, v246, 0
	v_fma_f32 v185, v101, v247, 0
	v_fmac_f32_e32 v184, v102, v248
	v_fmac_f32_e32 v185, v103, v249
	v_max_i32_e32 v246, 0, v208
	v_max_i32_e32 v247, 0, v200
	v_max_i32_e32 v248, 0, v209
	v_max_i32_e32 v249, 0, v201
	v_fmac_f32_e32 v184, v104, v246
	v_fmac_f32_e32 v185, v105, v247
	s_waitcnt lgkmcnt(6)
	v_mfma_f32_32x32x16_bf16 v[0:15], v[34:37], v[168:171], 0
	s_waitcnt vmcnt(3)
	ds_write_b128 v140, v[50:53] offset:8192
	s_add_i32 s4, s18, 5
	s_min_i32 s4, s4, s14
	v_mad_i64_i32 v[164:165], s[4:5], s4, v193, v[116:117]
	global_load_dwordx4 v[50:53], v[164:165], off
	v_fmac_f32_e32 v184, v106, v248
	v_fmac_f32_e32 v185, v107, v249
	v_max_i32_e32 v246, 0, v210
	v_max_i32_e32 v247, 0, v202
	v_max_i32_e32 v248, 0, v211
	v_max_i32_e32 v249, 0, v203
	v_fmac_f32_e32 v184, v108, v246
	v_fmac_f32_e32 v185, v109, v247
	v_fmac_f32_e32 v184, v110, v248
	v_fmac_f32_e32 v185, v111, v249
	s_waitcnt lgkmcnt(6)
	v_mfma_f32_32x32x16_bf16 v[16:31], v[38:41], v[172:175], v[16:31]
	v_max_i32_e32 v246, 0, v212
	v_max_i32_e32 v247, 0, v204
	v_max_i32_e32 v248, 0, v213
	v_max_i32_e32 v249, 0, v205
	v_fmac_f32_e32 v184, v112, v246
	v_fmac_f32_e32 v185, v113, v247
	v_fmac_f32_e32 v184, v114, v248
	v_fmac_f32_e32 v185, v115, v249
	s_waitcnt lgkmcnt(5)
	v_mfma_f32_32x32x16_bf16 v[0:15], v[38:41], v[176:179], v[0:15]
	v_cmp_le_f32_e64 s[52:53], v250, v185
	v_cmp_le_f32_e32 vcc, v156, v185
	s_andn2_b64 vcc, vcc, s[52:53]
	v_writelane_b32 v33, s52, 0
	v_writelane_b32 v33, s53, 4
	s_cbranch_vccz .Lp2_skip13
	v_mov_b32_e32 v246, vcc_hi
	v_mov_b32_e32 v247, vcc_lo
	v_cndmask_b32_e64 v246, v246, v247, s[48:49]
	s_and_saveexec_b64 s[4:5], vcc
	v_and_b32_e32 v247, v246, v127
	v_bcnt_u32_b32 v247, v247, v119
	v_cmp_gt_u32_e32 vcc, s35, v247
	v_ashrrev_i32_e32 v248, 31, v185
	v_add_u32_e32 v154, s0, v86
	v_bitop3_b32 v155, v185, v248, s97 bitop3:0x1e
	v_lshl_add_u32 v248, v247, 3, v160
	s_and_b64 exec, exec, vcc
	ds_write_b64 v248, v[154:155] offset:2048
	s_mov_b64 exec, s[4:5]
	v_bcnt_u32_b32 v119, v246, v119
.Lp2_skip13:
	s_waitcnt lgkmcnt(4)
	v_mfma_f32_32x32x16_bf16 v[16:31], v[42:45], v[230:233], v[16:31]
	v_cmp_le_f32_e64 s[52:53], v197, v184
	v_cmp_le_f32_e32 vcc, v157, v184
	s_andn2_b64 vcc, vcc, s[52:53]
	v_writelane_b32 v33, s52, 2
	v_writelane_b32 v33, s53, 6
	s_cbranch_vccz .Lp2_skip14
	v_mov_b32_e32 v246, vcc_hi
	v_mov_b32_e32 v247, vcc_lo
	v_cndmask_b32_e64 v246, v246, v247, s[48:49]
	s_and_saveexec_b64 s[4:5], vcc
	v_and_b32_e32 v247, v246, v127
	v_bcnt_u32_b32 v247, v247, v118
	v_cmp_gt_u32_e32 vcc, s35, v247
	v_ashrrev_i32_e32 v248, 31, v184
	v_add_u32_e32 v154, s0, v86
	v_bitop3_b32 v155, v184, v248, s97 bitop3:0x1e
	v_lshl_add_u32 v248, v247, 3, v161
	s_and_b64 exec, exec, vcc
	ds_write_b64 v248, v[154:155] offset:2048
	s_mov_b64 exec, s[4:5]
	v_bcnt_u32_b32 v118, v246, v118
.Lp2_skip14:
	v_max_i32_e32 v246, 0, v222
	v_max_i32_e32 v247, 0, v214
	s_waitcnt lgkmcnt(3)
	v_mfma_f32_32x32x16_bf16 v[0:15], v[42:45], v[234:237], v[0:15]
	v_max_i32_e32 v248, 0, v223
	v_max_i32_e32 v249, 0, v215
	v_fma_f32 v184, v100, v246, 0
	v_fma_f32 v185, v101, v247, 0
	v_fmac_f32_e32 v184, v102, v248
	v_fmac_f32_e32 v185, v103, v249
	v_max_i32_e32 v246, 0, v224
	v_max_i32_e32 v247, 0, v216
	v_max_i32_e32 v248, 0, v225
	v_max_i32_e32 v249, 0, v217
	s_waitcnt lgkmcnt(2)
	v_mfma_f32_32x32x16_bf16 v[16:31], v[46:49], v[238:241], v[16:31]
	v_fmac_f32_e32 v184, v104, v246
	v_fmac_f32_e32 v185, v105, v247
	v_fmac_f32_e32 v184, v106, v248
	v_fmac_f32_e32 v185, v107, v249
	v_max_i32_e32 v246, 0, v226
	v_max_i32_e32 v247, 0, v218
	v_max_i32_e32 v248, 0, v227
	v_max_i32_e32 v249, 0, v219
	v_fmac_f32_e32 v184, v108, v246
	v_fmac_f32_e32 v185, v109, v247
	s_waitcnt lgkmcnt(1)
	v_mfma_f32_32x32x16_bf16 v[0:15], v[46:49], v[242:245], v[0:15]
	v_fmac_f32_e32 v184, v110, v248
	v_fmac_f32_e32 v185, v111, v249
	v_max_i32_e32 v246, 0, v228
	v_max_i32_e32 v247, 0, v220
	v_max_i32_e32 v248, 0, v229
	v_max_i32_e32 v249, 0, v221
	v_fmac_f32_e32 v184, v112, v246
	v_fmac_f32_e32 v185, v113, v247
	v_fmac_f32_e32 v184, v114, v248
	v_fmac_f32_e32 v185, v115, v249
	v_cmp_le_f32_e64 s[52:53], v250, v185
	v_cmp_le_f32_e32 vcc, v156, v185
	s_andn2_b64 vcc, vcc, s[52:53]
	v_writelane_b32 v33, s52, 1
	v_writelane_b32 v33, s53, 5
	s_cbranch_vccz .Lp2_skip15
	v_mov_b32_e32 v246, vcc_hi
	v_mov_b32_e32 v247, vcc_lo
	v_cndmask_b32_e64 v246, v246, v247, s[48:49]
	s_and_saveexec_b64 s[4:5], vcc
	v_and_b32_e32 v247, v246, v127
	v_bcnt_u32_b32 v247, v247, v119
	v_cmp_gt_u32_e32 vcc, s35, v247
	v_ashrrev_i32_e32 v248, 31, v185
	v_add_u32_e32 v154, s0, v84
	v_bitop3_b32 v155, v185, v248, s97 bitop3:0x1e
	v_lshl_add_u32 v248, v247, 3, v160
	s_and_b64 exec, exec, vcc
	ds_write_b64 v248, v[154:155] offset:2048
	s_mov_b64 exec, s[4:5]
	v_bcnt_u32_b32 v119, v246, v119
.Lp2_skip15:
	v_cmp_le_f32_e64 s[52:53], v197, v184
	v_cmp_le_f32_e32 vcc, v157, v184
	s_andn2_b64 vcc, vcc, s[52:53]
	v_writelane_b32 v33, s52, 3
	v_writelane_b32 v33, s53, 7
	s_cbranch_vccz .Lp2_skip16
	v_mov_b32_e32 v246, vcc_hi
	v_mov_b32_e32 v247, vcc_lo
	v_cndmask_b32_e64 v246, v246, v247, s[48:49]
	s_and_saveexec_b64 s[4:5], vcc
	v_and_b32_e32 v247, v246, v127
	v_bcnt_u32_b32 v247, v247, v118
	v_cmp_gt_u32_e32 vcc, s35, v247
	v_ashrrev_i32_e32 v248, 31, v184
	v_add_u32_e32 v154, s0, v84
	v_bitop3_b32 v155, v184, v248, s97 bitop3:0x1e
	v_lshl_add_u32 v248, v247, 3, v161
	s_and_b64 exec, exec, vcc
	ds_write_b64 v248, v[154:155] offset:2048
	s_mov_b64 exec, s[4:5]
	v_bcnt_u32_b32 v118, v246, v118
.Lp2_skip16:
	ds_write_b32 v162, v33
	v_add_u32_e32 v162, 8, v162
	s_waitcnt lgkmcnt(0)
	s_barrier
	s_add_u32 s0, s0, 0xffffff00
	s_addc_u32 s1, s1, -1
	s_add_u32 s18, s18, 1
	s_cmp_ge_u32 s18, s13
	s_cbranch_scc1 .Lp2_drain0
	s_branch .Lp2_c1
.Lp2_drain0:
	v_max_i32_e32 v246, 0, v24
	v_max_i32_e32 v247, 0, v16
	v_max_i32_e32 v248, 0, v25
	v_max_i32_e32 v249, 0, v17
	v_fma_f32 v184, v100, v246, 0
	v_fma_f32 v185, v101, v247, 0
	v_fmac_f32_e32 v184, v102, v248
	v_fmac_f32_e32 v185, v103, v249
	v_max_i32_e32 v246, 0, v26
	v_max_i32_e32 v247, 0, v18
	v_max_i32_e32 v248, 0, v27
	v_max_i32_e32 v249, 0, v19
	v_fmac_f32_e32 v184, v104, v246
	v_fmac_f32_e32 v185, v105, v247
	v_fmac_f32_e32 v184, v106, v248
	v_fmac_f32_e32 v185, v107, v249
	v_max_i32_e32 v246, 0, v28
	v_max_i32_e32 v247, 0, v20
	v_max_i32_e32 v248, 0, v29
	v_max_i32_e32 v249, 0, v21
	v_fmac_f32_e32 v184, v108, v246
	v_fmac_f32_e32 v185, v109, v247
	v_fmac_f32_e32 v184, v110, v248
	v_fmac_f32_e32 v185, v111, v249
	v_max_i32_e32 v246, 0, v30
	v_max_i32_e32 v247, 0, v22
	v_max_i32_e32 v248, 0, v31
	v_max_i32_e32 v249, 0, v23
	v_fmac_f32_e32 v184, v112, v246
	v_fmac_f32_e32 v185, v113, v247
	v_fmac_f32_e32 v184, v114, v248
	v_fmac_f32_e32 v185, v115, v249
	v_cmp_le_f32_e64 s[52:53], v250, v185
	v_cmp_le_f32_e32 vcc, v156, v185
	s_andn2_b64 vcc, vcc, s[52:53]
	v_writelane_b32 v33, s52, 0
	v_writelane_b32 v33, s53, 4
	s_cbranch_vccz .Lp2_skip17
	v_mov_b32_e32 v246, vcc_hi
	v_mov_b32_e32 v247, vcc_lo
	v_cndmask_b32_e64 v246, v246, v247, s[48:49]
	s_and_saveexec_b64 s[4:5], vcc
	v_and_b32_e32 v247, v246, v127
	v_bcnt_u32_b32 v247, v247, v119
	v_cmp_gt_u32_e32 vcc, s35, v247
	v_ashrrev_i32_e32 v248, 31, v185
	v_add_u32_e32 v154, s0, v78
	v_bitop3_b32 v155, v185, v248, s97 bitop3:0x1e
	v_lshl_add_u32 v248, v247, 3, v160
	s_and_b64 exec, exec, vcc
	ds_write_b64 v248, v[154:155] offset:2048
	s_mov_b64 exec, s[4:5]
	v_bcnt_u32_b32 v119, v246, v119
.Lp2_skip17:
	v_cmp_le_f32_e64 s[52:53], v197, v184
	v_cmp_le_f32_e32 vcc, v157, v184
	s_andn2_b64 vcc, vcc, s[52:53]
	v_writelane_b32 v33, s52, 2
	v_writelane_b32 v33, s53, 6
	s_cbranch_vccz .Lp2_skip18
	v_mov_b32_e32 v246, vcc_hi
	v_mov_b32_e32 v247, vcc_lo
	v_cndmask_b32_e64 v246, v246, v247, s[48:49]
	s_and_saveexec_b64 s[4:5], vcc
	v_and_b32_e32 v247, v246, v127
	v_bcnt_u32_b32 v247, v247, v118
	v_cmp_gt_u32_e32 vcc, s35, v247
	v_ashrrev_i32_e32 v248, 31, v184
	v_add_u32_e32 v154, s0, v78
	v_bitop3_b32 v155, v184, v248, s97 bitop3:0x1e
	v_lshl_add_u32 v248, v247, 3, v161
	s_and_b64 exec, exec, vcc
	ds_write_b64 v248, v[154:155] offset:2048
	s_mov_b64 exec, s[4:5]
	v_bcnt_u32_b32 v118, v246, v118
.Lp2_skip18:
	v_max_i32_e32 v246, 0, v8
	v_max_i32_e32 v247, 0, v0
	v_max_i32_e32 v248, 0, v9
	v_max_i32_e32 v249, 0, v1
	v_fma_f32 v184, v100, v246, 0
	v_fma_f32 v185, v101, v247, 0
	v_fmac_f32_e32 v184, v102, v248
	v_fmac_f32_e32 v185, v103, v249
	v_max_i32_e32 v246, 0, v10
	v_max_i32_e32 v247, 0, v2
	v_max_i32_e32 v248, 0, v11
	v_max_i32_e32 v249, 0, v3
	v_fmac_f32_e32 v184, v104, v246
	v_fmac_f32_e32 v185, v105, v247
	v_fmac_f32_e32 v184, v106, v248
	v_fmac_f32_e32 v185, v107, v249
	v_max_i32_e32 v246, 0, v12
	v_max_i32_e32 v247, 0, v4
	v_max_i32_e32 v248, 0, v13
	v_max_i32_e32 v249, 0, v5
	v_fmac_f32_e32 v184, v108, v246
	v_fmac_f32_e32 v185, v109, v247
	v_fmac_f32_e32 v184, v110, v248
	v_fmac_f32_e32 v185, v111, v249
	v_max_i32_e32 v246, 0, v14
	v_max_i32_e32 v247, 0, v6
	v_max_i32_e32 v248, 0, v15
	v_max_i32_e32 v249, 0, v7
	v_fmac_f32_e32 v184, v112, v246
	v_fmac_f32_e32 v185, v113, v247
	v_fmac_f32_e32 v184, v114, v248
	v_fmac_f32_e32 v185, v115, v249
	v_cmp_le_f32_e64 s[52:53], v250, v185
	v_cmp_le_f32_e32 vcc, v156, v185
	s_andn2_b64 vcc, vcc, s[52:53]
	v_writelane_b32 v33, s52, 1
	v_writelane_b32 v33, s53, 5
	s_cbranch_vccz .Lp2_skip19
	v_mov_b32_e32 v246, vcc_hi
	v_mov_b32_e32 v247, vcc_lo
	v_cndmask_b32_e64 v246, v246, v247, s[48:49]
	s_and_saveexec_b64 s[4:5], vcc
	v_and_b32_e32 v247, v246, v127
	v_bcnt_u32_b32 v247, v247, v119
	v_cmp_gt_u32_e32 vcc, s35, v247
	v_ashrrev_i32_e32 v248, 31, v185
	v_add_u32_e32 v154, s0, v96
	v_bitop3_b32 v155, v185, v248, s97 bitop3:0x1e
	v_lshl_add_u32 v248, v247, 3, v160
	s_and_b64 exec, exec, vcc
	ds_write_b64 v248, v[154:155] offset:2048
	s_mov_b64 exec, s[4:5]
	v_bcnt_u32_b32 v119, v246, v119

.Lp2_skip20:
	ds_write_b32 v162, v33
	v_add_u32_e32 v162, 8, v162
	s_waitcnt lgkmcnt(0)
	s_barrier
	s_branch .LBB0_1140
.Lp2_drain1:
	v_max_i32_e32 v246, 0, v206
	v_max_i32_e32 v247, 0, v198
	v_max_i32_e32 v248, 0, v207
	v_max_i32_e32 v249, 0, v199
	v_fma_f32 v184, v100, v246, 0
	v_fma_f32 v185, v101, v247, 0
	v_fmac_f32_e32 v184, v102, v248
	v_fmac_f32_e32 v185, v103, v249
	v_max_i32_e32 v246, 0, v208
	v_max_i32_e32 v247, 0, v200
	v_max_i32_e32 v248, 0, v209
	v_max_i32_e32 v249, 0, v201
	v_fmac_f32_e32 v184, v104, v246
	v_fmac_f32_e32 v185, v105, v247
	v_fmac_f32_e32 v184, v106, v248
	v_fmac_f32_e32 v185, v107, v249
	v_max_i32_e32 v246, 0, v210
	v_max_i32_e32 v247, 0, v202
	v_max_i32_e32 v248, 0, v211
	v_max_i32_e32 v249, 0, v203
	v_fmac_f32_e32 v184, v108, v246
	v_fmac_f32_e32 v185, v109, v247
	v_fmac_f32_e32 v184, v110, v248
	v_fmac_f32_e32 v185, v111, v249
	v_max_i32_e32 v246, 0, v212
	v_max_i32_e32 v247, 0, v204
	v_max_i32_e32 v248, 0, v213
	v_max_i32_e32 v249, 0, v205
	v_fmac_f32_e32 v184, v112, v246
	v_fmac_f32_e32 v185, v113, v247
	v_fmac_f32_e32 v184, v114, v248
	v_fmac_f32_e32 v185, v115, v249
	v_cmp_le_f32_e64 s[52:53], v250, v185
	v_cmp_le_f32_e32 vcc, v156, v185
	s_andn2_b64 vcc, vcc, s[52:53]
	v_writelane_b32 v33, s52, 0
	v_writelane_b32 v33, s53, 4
	s_cbranch_vccz .Lp2_skip21
	v_mov_b32_e32 v246, vcc_hi
	v_mov_b32_e32 v247, vcc_lo
	v_cndmask_b32_e64 v246, v246, v247, s[48:49]
	s_and_saveexec_b64 s[4:5], vcc
	v_and_b32_e32 v247, v246, v127
	v_bcnt_u32_b32 v247, v247, v119
	v_cmp_gt_u32_e32 vcc, s35, v247
	v_ashrrev_i32_e32 v248, 31, v185
	v_add_u32_e32 v154, s0, v92
	v_bitop3_b32 v155, v185, v248, s97 bitop3:0x1e
	v_lshl_add_u32 v248, v247, 3, v160
	s_and_b64 exec, exec, vcc
	ds_write_b64 v248, v[154:155] offset:2048
	s_mov_b64 exec, s[4:5]
	v_bcnt_u32_b32 v119, v246, v119
.Lp2_skip21:
	v_cmp_le_f32_e64 s[52:53], v197, v184
	v_cmp_le_f32_e32 vcc, v157, v184
	s_andn2_b64 vcc, vcc, s[52:53]
	v_writelane_b32 v33, s52, 2
	v_writelane_b32 v33, s53, 6
	s_cbranch_vccz .Lp2_skip22
	v_mov_b32_e32 v246, vcc_hi
	v_mov_b32_e32 v247, vcc_lo
	v_cndmask_b32_e64 v246, v246, v247, s[48:49]
	s_and_saveexec_b64 s[4:5], vcc
	v_and_b32_e32 v247, v246, v127
	v_bcnt_u32_b32 v247, v247, v118
	v_cmp_gt_u32_e32 vcc, s35, v247
	v_ashrrev_i32_e32 v248, 31, v184
	v_add_u32_e32 v154, s0, v92
	v_bitop3_b32 v155, v184, v248, s97 bitop3:0x1e
	v_lshl_add_u32 v248, v247, 3, v161
	s_and_b64 exec, exec, vcc
	ds_write_b64 v248, v[154:155] offset:2048
	s_mov_b64 exec, s[4:5]
	v_bcnt_u32_b32 v118, v246, v118
.Lp2_skip22:
	v_max_i32_e32 v246, 0, v222
	v_max_i32_e32 v247, 0, v214
	v_max_i32_e32 v248, 0, v223
	v_max_i32_e32 v249, 0, v215
	v_fma_f32 v184, v100, v246, 0
	v_fma_f32 v185, v101, v247, 0
	v_fmac_f32_e32 v184, v102, v248
	v_fmac_f32_e32 v185, v103, v249
	v_max_i32_e32 v246, 0, v224
	v_max_i32_e32 v247, 0, v216
	v_max_i32_e32 v248, 0, v225
	v_max_i32_e32 v249, 0, v217
	v_fmac_f32_e32 v184, v104, v246
	v_fmac_f32_e32 v185, v105, v247
	v_fmac_f32_e32 v184, v106, v248
	v_fmac_f32_e32 v185, v107, v249
	v_max_i32_e32 v246, 0, v226
	v_max_i32_e32 v247, 0, v218
	v_max_i32_e32 v248, 0, v227
	v_max_i32_e32 v249, 0, v219
	v_fmac_f32_e32 v184, v108, v246
	v_fmac_f32_e32 v185, v109, v247
	v_fmac_f32_e32 v184, v110, v248
	v_fmac_f32_e32 v185, v111, v249
	v_max_i32_e32 v246, 0, v228
	v_max_i32_e32 v247, 0, v220
	v_max_i32_e32 v248, 0, v229
	v_max_i32_e32 v249, 0, v221
	v_fmac_f32_e32 v184, v112, v246
	v_fmac_f32_e32 v185, v113, v247
	v_fmac_f32_e32 v184, v114, v248
	v_fmac_f32_e32 v185, v115, v249
	v_cmp_le_f32_e64 s[52:53], v250, v185
	v_cmp_le_f32_e32 vcc, v156, v185
	s_andn2_b64 vcc, vcc, s[52:53]
	v_writelane_b32 v33, s52, 1
	v_writelane_b32 v33, s53, 5
	s_cbranch_vccz .Lp2_skip23
	v_mov_b32_e32 v246, vcc_hi
	v_mov_b32_e32 v247, vcc_lo
	v_cndmask_b32_e64 v246, v246, v247, s[48:49]
	s_and_saveexec_b64 s[4:5], vcc
	v_and_b32_e32 v247, v246, v127
	v_bcnt_u32_b32 v247, v247, v119
	v_cmp_gt_u32_e32 vcc, s35, v247
	v_ashrrev_i32_e32 v248, 31, v185
	v_add_u32_e32 v154, s0, v94
	v_bitop3_b32 v155, v185, v248, s97 bitop3:0x1e
	v_lshl_add_u32 v248, v247, 3, v160
	s_and_b64 exec, exec, vcc
	ds_write_b64 v248, v[154:155] offset:2048
	s_mov_b64 exec, s[4:5]
	v_bcnt_u32_b32 v119, v246, v119

.Lp2_drain2:
	v_max_i32_e32 v246, 0, v24
	v_max_i32_e32 v247, 0, v16
	v_max_i32_e32 v248, 0, v25
	v_max_i32_e32 v249, 0, v17
	v_fma_f32 v184, v100, v246, 0
	v_fma_f32 v185, v101, v247, 0
	v_fmac_f32_e32 v184, v102, v248
	v_fmac_f32_e32 v185, v103, v249
	v_max_i32_e32 v246, 0, v26
	v_max_i32_e32 v247, 0, v18
	v_max_i32_e32 v248, 0, v27
	v_max_i32_e32 v249, 0, v19
	v_fmac_f32_e32 v184, v104, v246
	v_fmac_f32_e32 v185, v105, v247
	v_fmac_f32_e32 v184, v106, v248
	v_fmac_f32_e32 v185, v107, v249
	v_max_i32_e32 v246, 0, v28
	v_max_i32_e32 v247, 0, v20
	v_max_i32_e32 v248, 0, v29
	v_max_i32_e32 v249, 0, v21
	v_fmac_f32_e32 v184, v108, v246
	v_fmac_f32_e32 v185, v109, v247
	v_fmac_f32_e32 v184, v110, v248
	v_fmac_f32_e32 v185, v111, v249
	v_max_i32_e32 v246, 0, v30
	v_max_i32_e32 v247, 0, v22
	v_max_i32_e32 v248, 0, v31
	v_max_i32_e32 v249, 0, v23
	v_fmac_f32_e32 v184, v112, v246
	v_fmac_f32_e32 v185, v113, v247
	v_fmac_f32_e32 v184, v114, v248
	v_fmac_f32_e32 v185, v115, v249
	v_cmp_le_f32_e64 s[52:53], v250, v185
	v_cmp_le_f32_e32 vcc, v156, v185
	s_andn2_b64 vcc, vcc, s[52:53]
	v_writelane_b32 v33, s52, 0
	v_writelane_b32 v33, s53, 4
	s_cbranch_vccz .Lp2_skip25
	v_mov_b32_e32 v246, vcc_hi
	v_mov_b32_e32 v247, vcc_lo
	v_cndmask_b32_e64 v246, v246, v247, s[48:49]
	s_and_saveexec_b64 s[4:5], vcc
	v_and_b32_e32 v247, v246, v127
	v_bcnt_u32_b32 v247, v247, v119
	v_cmp_gt_u32_e32 vcc, s35, v247
	v_ashrrev_i32_e32 v248, 31, v185
	v_add_u32_e32 v154, s0, v90
	v_bitop3_b32 v155, v185, v248, s97 bitop3:0x1e
	v_lshl_add_u32 v248, v247, 3, v160
	s_and_b64 exec, exec, vcc
	ds_write_b64 v248, v[154:155] offset:2048
	s_mov_b64 exec, s[4:5]
	v_bcnt_u32_b32 v119, v246, v119
.Lp2_skip25:
	v_cmp_le_f32_e64 s[52:53], v197, v184
	v_cmp_le_f32_e32 vcc, v157, v184
	s_andn2_b64 vcc, vcc, s[52:53]
	v_writelane_b32 v33, s52, 2
	v_writelane_b32 v33, s53, 6
	s_cbranch_vccz .Lp2_skip26
	v_mov_b32_e32 v246, vcc_hi
	v_mov_b32_e32 v247, vcc_lo
	v_cndmask_b32_e64 v246, v246, v247, s[48:49]
	s_and_saveexec_b64 s[4:5], vcc
	v_and_b32_e32 v247, v246, v127
	v_bcnt_u32_b32 v247, v247, v118
	v_cmp_gt_u32_e32 vcc, s35, v247
	v_ashrrev_i32_e32 v248, 31, v184
	v_add_u32_e32 v154, s0, v90
	v_bitop3_b32 v155, v184, v248, s97 bitop3:0x1e
	v_lshl_add_u32 v248, v247, 3, v161
	s_and_b64 exec, exec, vcc
	ds_write_b64 v248, v[154:155] offset:2048
	s_mov_b64 exec, s[4:5]
	v_bcnt_u32_b32 v118, v246, v118
.Lp2_skip26:
	v_max_i32_e32 v246, 0, v8
	v_max_i32_e32 v247, 0, v0
	v_max_i32_e32 v248, 0, v9
	v_max_i32_e32 v249, 0, v1
	v_fma_f32 v184, v100, v246, 0
	v_fma_f32 v185, v101, v247, 0
	v_fmac_f32_e32 v184, v102, v248
	v_fmac_f32_e32 v185, v103, v249
	v_max_i32_e32 v246, 0, v10
	v_max_i32_e32 v247, 0, v2
	v_max_i32_e32 v248, 0, v11
	v_max_i32_e32 v249, 0, v3
	v_fmac_f32_e32 v184, v104, v246
	v_fmac_f32_e32 v185, v105, v247
	v_fmac_f32_e32 v184, v106, v248
	v_fmac_f32_e32 v185, v107, v249
	v_max_i32_e32 v246, 0, v12
	v_max_i32_e32 v247, 0, v4
	v_max_i32_e32 v248, 0, v13
	v_max_i32_e32 v249, 0, v5
	v_fmac_f32_e32 v184, v108, v246
	v_fmac_f32_e32 v185, v109, v247
	v_fmac_f32_e32 v184, v110, v248
	v_fmac_f32_e32 v185, v111, v249
	v_max_i32_e32 v246, 0, v14
	v_max_i32_e32 v247, 0, v6
	v_max_i32_e32 v248, 0, v15
	v_max_i32_e32 v249, 0, v7
	v_fmac_f32_e32 v184, v112, v246
	v_fmac_f32_e32 v185, v113, v247
	v_fmac_f32_e32 v184, v114, v248
	v_fmac_f32_e32 v185, v115, v249
	v_cmp_le_f32_e64 s[52:53], v250, v185
	v_cmp_le_f32_e32 vcc, v156, v185
	s_andn2_b64 vcc, vcc, s[52:53]
	v_writelane_b32 v33, s52, 1
	v_writelane_b32 v33, s53, 5
	s_cbranch_vccz .Lp2_skip27
	v_mov_b32_e32 v246, vcc_hi
	v_mov_b32_e32 v247, vcc_lo
	v_cndmask_b32_e64 v246, v246, v247, s[48:49]
	s_and_saveexec_b64 s[4:5], vcc
	v_and_b32_e32 v247, v246, v127
	v_bcnt_u32_b32 v247, v247, v119
	v_cmp_gt_u32_e32 vcc, s35, v247
	v_ashrrev_i32_e32 v248, 31, v185
	v_add_u32_e32 v154, s0, v88
	v_bitop3_b32 v155, v185, v248, s97 bitop3:0x1e
	v_lshl_add_u32 v248, v247, 3, v160
	s_and_b64 exec, exec, vcc
	ds_write_b64 v248, v[154:155] offset:2048
	s_mov_b64 exec, s[4:5]
	v_bcnt_u32_b32 v119, v246, v119

.Lp2_drain3:
	v_max_i32_e32 v246, 0, v206
	v_max_i32_e32 v247, 0, v198
	v_max_i32_e32 v248, 0, v207
	v_max_i32_e32 v249, 0, v199
	v_fma_f32 v184, v100, v246, 0
	v_fma_f32 v185, v101, v247, 0
	v_fmac_f32_e32 v184, v102, v248
	v_fmac_f32_e32 v185, v103, v249
	v_max_i32_e32 v246, 0, v208
	v_max_i32_e32 v247, 0, v200
	v_max_i32_e32 v248, 0, v209
	v_max_i32_e32 v249, 0, v201
	v_fmac_f32_e32 v184, v104, v246
	v_fmac_f32_e32 v185, v105, v247
	v_fmac_f32_e32 v184, v106, v248
	v_fmac_f32_e32 v185, v107, v249
	v_max_i32_e32 v246, 0, v210
	v_max_i32_e32 v247, 0, v202
	v_max_i32_e32 v248, 0, v211
	v_max_i32_e32 v249, 0, v203
	v_fmac_f32_e32 v184, v108, v246
	v_fmac_f32_e32 v185, v109, v247
	v_fmac_f32_e32 v184, v110, v248
	v_fmac_f32_e32 v185, v111, v249
	v_max_i32_e32 v246, 0, v212
	v_max_i32_e32 v247, 0, v204
	v_max_i32_e32 v248, 0, v213
	v_max_i32_e32 v249, 0, v205
	v_fmac_f32_e32 v184, v112, v246
	v_fmac_f32_e32 v185, v113, v247
	v_fmac_f32_e32 v184, v114, v248
	v_fmac_f32_e32 v185, v115, v249
	v_cmp_le_f32_e64 s[52:53], v250, v185
	v_cmp_le_f32_e32 vcc, v156, v185
	s_andn2_b64 vcc, vcc, s[52:53]
	v_writelane_b32 v33, s52, 0
	v_writelane_b32 v33, s53, 4
	s_cbranch_vccz .Lp2_skip29
	v_mov_b32_e32 v246, vcc_hi
	v_mov_b32_e32 v247, vcc_lo
	v_cndmask_b32_e64 v246, v246, v247, s[48:49]
	s_and_saveexec_b64 s[4:5], vcc
	v_and_b32_e32 v247, v246, v127
	v_bcnt_u32_b32 v247, v247, v119
	v_cmp_gt_u32_e32 vcc, s35, v247
	v_ashrrev_i32_e32 v248, 31, v185
	v_add_u32_e32 v154, s0, v86
	v_bitop3_b32 v155, v185, v248, s97 bitop3:0x1e
	v_lshl_add_u32 v248, v247, 3, v160
	s_and_b64 exec, exec, vcc
	ds_write_b64 v248, v[154:155] offset:2048
	s_mov_b64 exec, s[4:5]
	v_bcnt_u32_b32 v119, v246, v119
.Lp2_skip29:
	v_cmp_le_f32_e64 s[52:53], v197, v184
	v_cmp_le_f32_e32 vcc, v157, v184
	s_andn2_b64 vcc, vcc, s[52:53]
	v_writelane_b32 v33, s52, 2
	v_writelane_b32 v33, s53, 6
	s_cbranch_vccz .Lp2_skip30
	v_mov_b32_e32 v246, vcc_hi
	v_mov_b32_e32 v247, vcc_lo
	v_cndmask_b32_e64 v246, v246, v247, s[48:49]
	s_and_saveexec_b64 s[4:5], vcc
	v_and_b32_e32 v247, v246, v127
	v_bcnt_u32_b32 v247, v247, v118
	v_cmp_gt_u32_e32 vcc, s35, v247
	v_ashrrev_i32_e32 v248, 31, v184
	v_add_u32_e32 v154, s0, v86
	v_bitop3_b32 v155, v184, v248, s97 bitop3:0x1e
	v_lshl_add_u32 v248, v247, 3, v161
	s_and_b64 exec, exec, vcc
	ds_write_b64 v248, v[154:155] offset:2048
	s_mov_b64 exec, s[4:5]
	v_bcnt_u32_b32 v118, v246, v118
.Lp2_skip30:
	v_max_i32_e32 v246, 0, v222
	v_max_i32_e32 v247, 0, v214
	v_max_i32_e32 v248, 0, v223
	v_max_i32_e32 v249, 0, v215
	v_fma_f32 v184, v100, v246, 0
	v_fma_f32 v185, v101, v247, 0
	v_fmac_f32_e32 v184, v102, v248
	v_fmac_f32_e32 v185, v103, v249
	v_max_i32_e32 v246, 0, v224
	v_max_i32_e32 v247, 0, v216
	v_max_i32_e32 v248, 0, v225
	v_max_i32_e32 v249, 0, v217
	v_fmac_f32_e32 v184, v104, v246
	v_fmac_f32_e32 v185, v105, v247
	v_fmac_f32_e32 v184, v106, v248
	v_fmac_f32_e32 v185, v107, v249
	v_max_i32_e32 v246, 0, v226
	v_max_i32_e32 v247, 0, v218
	v_max_i32_e32 v248, 0, v227
	v_max_i32_e32 v249, 0, v219
	v_fmac_f32_e32 v184, v108, v246
	v_fmac_f32_e32 v185, v109, v247
	v_fmac_f32_e32 v184, v110, v248
	v_fmac_f32_e32 v185, v111, v249
	v_max_i32_e32 v246, 0, v228
	v_max_i32_e32 v247, 0, v220
	v_max_i32_e32 v248, 0, v229
	v_max_i32_e32 v249, 0, v221
	v_fmac_f32_e32 v184, v112, v246
	v_fmac_f32_e32 v185, v113, v247
	v_fmac_f32_e32 v184, v114, v248
	v_fmac_f32_e32 v185, v115, v249
	v_cmp_le_f32_e64 s[52:53], v250, v185
	v_cmp_le_f32_e32 vcc, v156, v185
	s_andn2_b64 vcc, vcc, s[52:53]
	v_writelane_b32 v33, s52, 1
	v_writelane_b32 v33, s53, 5
	s_cbranch_vccz .Lp2_skip31
	v_mov_b32_e32 v246, vcc_hi
	v_mov_b32_e32 v247, vcc_lo
	v_cndmask_b32_e64 v246, v246, v247, s[48:49]
	s_and_saveexec_b64 s[4:5], vcc
	v_and_b32_e32 v247, v246, v127
	v_bcnt_u32_b32 v247, v247, v119
	v_cmp_gt_u32_e32 vcc, s35, v247
	v_ashrrev_i32_e32 v248, 31, v185
	v_add_u32_e32 v154, s0, v84
	v_bitop3_b32 v155, v185, v248, s97 bitop3:0x1e
	v_lshl_add_u32 v248, v247, 3, v160
	s_and_b64 exec, exec, vcc
	ds_write_b64 v248, v[154:155] offset:2048
	s_mov_b64 exec, s[4:5]
	v_bcnt_u32_b32 v119, v246, v119
